# attention work queues: static first unit = wave*32 + (blockIdx>>3), so every CU (and each SIMD's two waves) starts with a mix of heavy and light units, on top of v29
# speedup vs baseline: 1.0117x; 1.0023x over previous
.LBB0_346:
	s_or_b64 exec, exec, s[4:5]
	s_xor_b64 s[46:47], s[0:1], -1
	s_lshl_b32 s0, s48, 9
	v_readlane_b32 s1, v254, 57
	s_or_b32 s76, s0, s1
	v_mov_b32_e32 v0, v236
	s_mov_b64 s[0:1], s[38:39]
	s_waitcnt lgkmcnt(0)
	s_barrier
	s_load_dwordx2 s[4:5], s[0:1], 0x80
	v_readfirstlane_b32 s3, v0
	s_lshl_b32 s3, s3, 8
	s_and_b32 s3, s3, 0xffffc000
	s_add_i32 s49, s3, 0
	s_lshl_b64 s[6:7], s[76:77], 2
	s_waitcnt lgkmcnt(0)
	s_add_u32 s3, s4, s6
	s_addc_u32 s4, s5, s7
	v_readlane_b32 s5, v254, 27
	v_and_b32_e32 v246, 63, v0
	s_add_u32 s40, s3, s5
	s_addc_u32 s41, s4, 0
	v_cmp_eq_u32_e64 s[18:19], 0, v246
	v_readfirstlane_b32 s99, v236
	s_lshr_b32 s99, s99, 6
	s_lshl_b32 s99, s99, 5
	s_lshr_b32 s100, s2, 3
	s_add_i32 s99, s99, s100
	s_branch .LBB0_350
